# v31: v30 + P4 even workgroups also run their sample-row tail tile after their GEMM tiles (odd: conversion + tail first)
# speedup vs baseline: 1.0239x; 1.0007x over previous
; #define LAS __attribute__((address_space(3)))
; __device__ __forceinline__ int permrow(int n) { return (n & ~255) | ((((n >> 5) & 1) * 128) + (((n >> 6) & 3) * 32) + (n & 31)); }
; template <int KSTEPS>
; __device__ __forceinline__ void tail_partial(const bf16_t* A, int lda, const bf16_t* Bt, int ldb, int col0, LAS float* part, int lane) {
;     const int fr = lane & 15, fq = lane >> 4;
;     f32x4 acc[2][4];
; #pragma unroll
;     for (int m = 0; m < 2; ++m)
; #pragma unroll
;         for (int n = 0; n < 4; ++n) acc[m][n] = (f32x4){0.f, 0.f, 0.f, 0.f};
;     const bf16_t* ap = A + (size_t)fr * lda + 8 * fq;
;     const bf16_t* bp[4];
; #pragma unroll
;     for (int n = 0; n < 4; ++n) bp[n] = Bt + (size_t)permrow(col0 + 16 * n + fr) * ldb + 8 * fq;
; #pragma unroll
;     for (int ks = 0; ks < KSTEPS; ++ks) {
;         bf16x8 a[2], b[4];
; #pragma unroll
;         for (int m = 0; m < 2; ++m) a[m] = *(const bf16x8*)(ap + (size_t)(16 * m) * lda + 32 * ks);
; #pragma unroll
;         for (int n = 0; n < 4; ++n) b[n] = *(const bf16x8*)(bp[n] + 32 * ks);
; __global__ void __launch_bounds__(NWAVES * 64, 2) fwd_megakernel(Args args) {
;     ...
;             const int tm = bx >> 4, tn = bx & 15, row0 = MP + 32 * tm, col0 = 64 * tn, kw = wave * 128;
;             LAS float* parts = (LAS float*)lds;
;             tail_partial<4>(R1 + (size_t)row0 * DM + kw, DM, Wout_t + kw, DM, col0, parts + wave * 2048, lane);
;             __syncthreads();
;             const f32x4 cc = tail_sum(parts, 0, 8, tid);
;             const int r = row0 + (tid >> 4), c = col0 + (tid & 15) * 4;
;             const f32x4 h = cc + *(const f32x4*)(x_sample + (size_t)(r - MP) * DM + c);
.Lp4s_skip:
	s_mov_b32 s44, 0
	v_readlane_b32 s12, v254, 19
	v_readlane_b32 s13, v254, 20
	s_and_b64 vcc, exec, s[12:13]
	s_cbranch_vccz .Lp4t_skip
	s_bitcmp1_b32 s94, 0
	s_cbranch_scc0 .Lp4t_skip
.Lp4t_early:
	s_ashr_i32 s85, s84, 31
	s_and_b32 s11, s94, 15
	s_lshl_b32 s12, s11, 6
	s_lshl_b64 s[14:15], s[84:85], 11
	s_add_u32 s11, s80, s14
	s_addc_u32 s13, s81, s15
	s_lshl_b32 s14, s94, 5
	s_and_b32 s15, s14, 0x60
	s_lshl_b32 s16, s2, 7
	s_ashr_i32 s17, s16, 31
	s_lshl_b64 s[18:19], s[16:17], 1
	s_add_u32 s16, s11, s18
	s_addc_u32 s17, s13, s19
	s_add_u32 s26, s96, s18
	v_and_b32_e32 v86, 15, v1
	v_mov_b32_e32 v89, 0
	s_addc_u32 s27, s97, s19
	s_and_b32 s11, s12, 0x300
	v_lshlrev_b32_e32 v90, 11, v86
	v_mov_b32_e32 v91, v89
	v_and_b32_e32 v88, 48, v1
	s_or_b32 s13, s11, s15
	v_lshl_add_u64 v[92:93], s[16:17], 0, v[90:91]
	v_or_b32_e32 v87, s13, v86
	v_lshl_add_u64 v[90:91], v[92:93], 0, v[88:89]
	s_mov_b32 s11, 0x8000
	v_lshl_add_u64 v[92:93], s[26:27], 0, v[88:89]
	v_lshlrev_b32_e32 v94, 11, v87
	v_mov_b32_e32 v95, v89
	v_add_co_u32_e32 v96, vcc, s11, v90
	s_nop 1
	v_lshl_add_u64 v[98:99], v[92:93], 0, v[94:95]
	v_addc_co_u32_e32 v97, vcc, 0, v91, vcc
	s_nop 1
	v_add_co_u32_e32 v92, vcc, s11, v98
	s_nop 1
	s_mov_b32 s11, 0x40000
	v_addc_co_u32_e32 v93, vcc, 0, v99, vcc
	s_nop 1
	v_add_co_u32_e32 v94, vcc, s11, v98
	s_nop 1
	global_load_dwordx4 v[100:103], v[98:99], off
	global_load_dwordx4 v[104:107], v[98:99], off offset:64
	v_addc_co_u32_e32 v95, vcc, 0, v99, vcc
	s_nop 1
	global_load_dwordx4 v[108:111], v[96:97], off
	global_load_dwordx4 v[112:115], v[92:93], off
	global_load_dwordx4 v[116:119], v[94:95], off
	s_mov_b32 s11, 0x48000
	v_add_co_u32_e32 v120, vcc, s11, v98
	s_nop 1
	global_load_dwordx4 v[124:127], v[90:91], off
	global_load_dwordx4 v[128:131], v[90:91], off offset:64
	v_addc_co_u32_e32 v121, vcc, 0, v99, vcc
	s_nop 1
	global_load_dwordx4 v[132:135], v[120:121], off
	global_load_dwordx4 v[136:139], v[96:97], off offset:64
	global_load_dwordx4 v[140:143], v[92:93], off offset:64
	global_load_dwordx4 v[144:147], v[94:95], off offset:64
	global_load_dwordx4 v[148:151], v[120:121], off offset:64
	global_load_dwordx4 v[152:155], v[98:99], off offset:128
	global_load_dwordx4 v[156:159], v[90:91], off offset:128
	global_load_dwordx4 v[160:163], v[96:97], off offset:128
	global_load_dwordx4 v[164:167], v[92:93], off offset:128
	global_load_dwordx4 v[168:171], v[94:95], off offset:128
	global_load_dwordx4 v[172:175], v[90:91], off offset:192
	global_load_dwordx4 v[176:179], v[98:99], off offset:192
	global_load_dwordx4 v[180:183], v[120:121], off offset:128
	global_load_dwordx4 v[184:187], v[96:97], off offset:192
	global_load_dwordx4 v[96:99], v[120:121], off offset:192
	global_load_dwordx4 v[120:123], v[92:93], off offset:192
	global_load_dwordx4 v[188:191], v[94:95], off offset:192
	v_lshl_or_b32 v87, v86, 2, s12
	v_ashrrev_i32_e32 v86, 4, v1
	v_add_u32_e32 v90, s92, v86
	v_ashrrev_i32_e32 v91, 31, v90
	v_lshlrev_b64 v[92:93], 12, v[90:91]
	v_lshl_add_u64 v[90:91], s[66:67], 0, v[92:93]
	v_lshlrev_b32_e32 v86, 2, v87
	v_mov_b32_e32 v92, v86
	v_mov_b32_e32 v93, v89
	v_lshl_add_u64 v[94:95], v[90:91], 0, v[92:93]
	global_load_dwordx4 v[88:91], v[94:95], off
.Lp4t_skip:
	s_cmp_eq_u32 s44, 1
	s_cbranch_scc1 .Lp4_main
	s_cmpk_gt_i32 s3, 0x1fff
	s_cbranch_scc1 .LBB0_881
	s_bitcmp1_b32 s94, 0
	s_cbranch_scc0 .LBB0_881
	s_mov_b32 s40, s3
	s_mov_b32 s41, 1

; #define LAS __attribute__((address_space(3)))
; __device__ __forceinline__ int permrow(int n) { return (n & ~255) | ((((n >> 5) & 1) * 128) + (((n >> 6) & 3) * 32) + (n & 31)); }
; template <int KSTEPS>
; __device__ __forceinline__ void tail_partial(const bf16_t* A, int lda, const bf16_t* Bt, int ldb, int col0, LAS float* part, int lane) {
;     const int fr = lane & 15, fq = lane >> 4;
;     f32x4 acc[2][4];
; #pragma unroll
;     for (int m = 0; m < 2; ++m)
; #pragma unroll
;         for (int n = 0; n < 4; ++n) acc[m][n] = (f32x4){0.f, 0.f, 0.f, 0.f};
;     const bf16_t* ap = A + (size_t)fr * lda + 8 * fq;
;     const bf16_t* bp[4];
; #pragma unroll
;     for (int n = 0; n < 4; ++n) bp[n] = Bt + (size_t)permrow(col0 + 16 * n + fr) * ldb + 8 * fq;
; #pragma unroll
;     for (int ks = 0; ks < KSTEPS; ++ks) {
;         bf16x8 a[2], b[4];
; #pragma unroll
;         for (int m = 0; m < 2; ++m) a[m] = *(const bf16x8*)(ap + (size_t)(16 * m) * lda + 32 * ks);
; #pragma unroll
;         for (int n = 0; n < 4; ++n) b[n] = *(const bf16x8*)(bp[n] + 32 * ks);
; #pragma unroll
;         for (int m = 0; m < 2; ++m)
; #pragma unroll
;             for (int n = 0; n < 4; ++n) acc[m][n] = __builtin_amdgcn_mfma_f32_16x16x32_bf16(b[n], a[m], acc[m][n], 0, 0, 0);
;     }
; #pragma unroll
;     for (int m = 0; m < 2; ++m)
; #pragma unroll
;         for (int n = 0; n < 4; ++n) *(LAS f32x4*)(part + (16 * m + fr) * 64 + 16 * n + 4 * fq) = acc[m][n];
; __global__ void __launch_bounds__(NWAVES * 64, 2) fwd_megakernel(Args args) {
;     ...
;             const int tm = bx >> 4, tn = bx & 15, row0 = MP + 32 * tm, col0 = 64 * tn, kw = wave * 128;
;             LAS float* parts = (LAS float*)lds;
;             tail_partial<4>(R1 + (size_t)row0 * DM + kw, DM, Wout_t + kw, DM, col0, parts + wave * 2048, lane);
;             __syncthreads();
.LBB0_884:
	v_readlane_b32 s0, v254, 19
	s_add_u32 s8, s62, 0x1400000
	v_readlane_b32 s1, v254, 20
	s_addc_u32 s9, s63, 0
	s_ashr_i32 s85, s84, 31
	s_movk_i32 s24, 0x82
	s_and_b64 vcc, exec, s[0:1]
	s_cbranch_vccz .LBB0_888
	s_bitcmp1_b32 s94, 0
	s_cbranch_scc1 .Lp4_main
	s_movk_i32 s24, 0x80
	s_branch .LBB0_888
.Lp4_main:
	s_and_b32 s3, s94, 15
	s_lshl_b32 s0, s3, 6
	s_lshl_b64 s[4:5], s[84:85], 11
	s_add_u32 s1, s80, s4
	s_addc_u32 s7, s81, s5
	s_lshl_b32 s4, s94, 5
	s_and_b32 s10, s4, 0x60
	s_lshl_b32 s4, s2, 7
	s_ashr_i32 s5, s4, 31
	s_lshl_b64 s[4:5], s[4:5], 1
	s_add_u32 s6, s1, s4
	s_addc_u32 s7, s7, s5
	s_add_u32 s4, s96, s4
	v_and_b32_e32 v80, 15, v1
	v_mov_b32_e32 v3, 0
	s_addc_u32 s5, s97, s5
	s_and_b32 s1, s0, 0x300
	v_lshlrev_b32_e32 v8, 11, v80
	v_mov_b32_e32 v9, v3
	v_and_b32_e32 v2, 48, v1
	s_or_b32 s1, s1, s10
	v_lshl_add_u64 v[8:9], s[6:7], 0, v[8:9]
	v_or_b32_e32 v6, s1, v80
	v_lshl_add_u64 v[66:67], v[8:9], 0, v[2:3]
	s_mov_b32 s1, 0x8000
	v_lshl_add_u64 v[4:5], s[4:5], 0, v[2:3]
	v_lshlrev_b32_e32 v6, 11, v6
	v_mov_b32_e32 v7, v3
	v_add_co_u32_e32 v68, vcc, s1, v66
	v_lshl_add_u64 v[64:65], v[4:5], 0, v[6:7]
	s_nop 0
	v_addc_co_u32_e32 v69, vcc, 0, v67, vcc
	v_add_co_u32_e32 v72, vcc, s1, v64
	s_mov_b32 s4, 0x40000
	s_nop 0
	v_addc_co_u32_e32 v73, vcc, 0, v65, vcc
	v_add_co_u32_e32 v74, vcc, s4, v64
	s_nop 0
	s_nop 0
	v_addc_co_u32_e32 v75, vcc, 0, v65, vcc
	s_nop 0
	s_nop 0
	s_nop 0
	s_mov_b32 s1, 0x48000
	v_add_co_u32_e32 v76, vcc, s1, v64
	s_nop 0
	s_nop 0
	v_addc_co_u32_e32 v77, vcc, 0, v65, vcc
	s_nop 0
	s_nop 0
	s_nop 0
	s_nop 0
	s_nop 0
	s_lshl_b32 s1, s2, 13
	s_add_i32 s1, s1, 0
	s_nop 0
	s_waitcnt vmcnt(19)
	v_mfma_f32_16x16x32_bf16 v[32:35], v[100:103], v[124:127], 0
	v_mfma_f32_16x16x32_bf16 v[4:7], v[100:103], v[108:111], 0
	v_mfma_f32_16x16x32_bf16 v[48:51], v[112:115], v[124:127], 0
	v_mfma_f32_16x16x32_bf16 v[56:59], v[116:119], v[124:127], 0
	s_nop 0
	s_waitcnt vmcnt(17)
	v_mfma_f32_16x16x32_bf16 v[8:11], v[132:135], v[124:127], 0
	v_mfma_f32_16x16x32_bf16 v[16:19], v[112:115], v[108:111], 0
	v_mfma_f32_16x16x32_bf16 v[20:23], v[116:119], v[108:111], 0
	v_mfma_f32_16x16x32_bf16 v[12:15], v[132:135], v[108:111], 0
	v_mfma_f32_16x16x32_bf16 v[32:35], v[104:107], v[128:131], v[32:35]
	s_nop 0
	s_waitcnt vmcnt(16)
	v_mfma_f32_16x16x32_bf16 v[4:7], v[104:107], v[136:139], v[4:7]
	s_nop 0
	s_waitcnt vmcnt(15)
	v_mfma_f32_16x16x32_bf16 v[28:31], v[140:143], v[128:131], v[48:51]
	s_nop 0
	s_waitcnt vmcnt(14)
	v_mfma_f32_16x16x32_bf16 v[36:39], v[144:147], v[128:131], v[56:59]
	s_nop 0
	s_waitcnt vmcnt(13)
	v_mfma_f32_16x16x32_bf16 v[8:11], v[148:151], v[128:131], v[8:11]
	s_nop 0
	v_mfma_f32_16x16x32_bf16 v[16:19], v[140:143], v[136:139], v[16:19]
	s_nop 0
	s_nop 0
	v_mfma_f32_16x16x32_bf16 v[20:23], v[144:147], v[136:139], v[20:23]
	s_nop 0
	v_mfma_f32_16x16x32_bf16 v[12:15], v[148:151], v[136:139], v[12:15]
	s_nop 0
	s_nop 0
	s_nop 0
	s_nop 0
	s_nop 0
	s_nop 0
	s_nop 0
	s_nop 0
	s_waitcnt vmcnt(11)
	v_mfma_f32_16x16x32_bf16 v[32:35], v[152:155], v[156:159], v[32:35]
	s_nop 0
	s_nop 0
	s_waitcnt vmcnt(10)
	v_mfma_f32_16x16x32_bf16 v[4:7], v[152:155], v[160:163], v[4:7]
	s_nop 0
	s_nop 0
	s_nop 0
	s_nop 0
	s_waitcnt vmcnt(9)
	v_mfma_f32_16x16x32_bf16 v[28:31], v[164:167], v[156:159], v[28:31]
	s_nop 0
	s_waitcnt vmcnt(8)
	v_mfma_f32_16x16x32_bf16 v[36:39], v[168:171], v[156:159], v[36:39]
	s_nop 0
	s_waitcnt vmcnt(5)
	v_mfma_f32_16x16x32_bf16 v[8:11], v[180:183], v[156:159], v[8:11]
	v_lshl_or_b32 v44, v80, 2, s0
	s_movk_i32 s0, 0xa00
	v_mfma_f32_16x16x32_bf16 v[16:19], v[164:167], v[160:163], v[16:19]
	v_mfma_f32_16x16x32_bf16 v[20:23], v[168:171], v[160:163], v[20:23]
	v_lshlrev_b32_e32 v40, 8, v80
	v_add3_u32 v2, s1, v40, v2
	v_mov_b64_e32 v[42:43], s[82:83]
	v_mfma_f32_16x16x32_bf16 v[32:35], v[176:179], v[172:175], v[32:35]
	s_nop 0
	s_waitcnt vmcnt(2)
	v_mfma_f32_16x16x32_bf16 v[28:31], v[120:123], v[172:175], v[28:31]
	s_nop 5
	ds_write_b128 v2, v[32:35]
	s_nop 0
	s_waitcnt vmcnt(1)
	v_mfma_f32_16x16x32_bf16 v[36:39], v[188:191], v[172:175], v[36:39]
	v_mfma_f32_16x16x32_bf16 v[12:15], v[180:183], v[160:163], v[12:15]
	v_mfma_f32_16x16x32_bf16 v[8:11], v[96:99], v[172:175], v[8:11]
	ds_write_b128 v2, v[28:31] offset:64
	s_nop 4
	ds_write_b128 v2, v[36:39] offset:128
	s_nop 0
	ds_write_b128 v2, v[8:11] offset:192
	v_mfma_f32_16x16x32_bf16 v[4:7], v[176:179], v[184:187], v[4:7]
	v_mfma_f32_16x16x32_bf16 v[16:19], v[120:123], v[184:187], v[16:19]
	v_mfma_f32_16x16x32_bf16 v[8:11], v[188:191], v[184:187], v[20:23]
	s_nop 5
	ds_write_b128 v2, v[4:7] offset:4096
	ds_write_b128 v2, v[16:19] offset:4160
	ds_write_b128 v2, v[8:11] offset:4224
	v_ashrrev_i32_e32 v10, 4, v1
	v_mfma_f32_16x16x32_bf16 v[4:7], v[96:99], v[184:187], v[12:15]
	v_lshl_add_u32 v1, v1, 4, 0
	s_nop 6
	ds_write_b128 v2, v[4:7] offset:4288
	v_add_u32_e32 v4, s92, v10
	v_ashrrev_i32_e32 v5, 31, v4
	v_lshlrev_b64 v[4:5], 12, v[4:5]
	v_lshl_add_u64 v[4:5], s[66:67], 0, v[4:5]
	v_lshlrev_b32_e32 v2, 2, v44
	v_lshl_add_u64 v[4:5], v[4:5], 0, v[2:3]
	s_waitcnt lgkmcnt(0)
	s_barrier
; #define LAS __attribute__((address_space(3)))
; __device__ __forceinline__ unsigned cvt_pk_bf16(float lo, float hi) { const f32x2_t v = {lo, hi}; const bf16x2_t b = __builtin_convertvector(v, bf16x2_t); return __builtin_bit_cast(unsigned, b); }
; __device__ __forceinline__ f32x4 tail_sum(const LAS float* parts, int w0, int w1, int tid) {
;     f32x4 s = (f32x4){0.f, 0.f, 0.f, 0.f};
;     for (int w = w0; w < w1; ++w) s += *(const LAS f32x4*)(parts + w * 2048 + tid * 4);
;     return s;
; __global__ void __launch_bounds__(NWAVES * 64, 2) fwd_megakernel(Args args) {
;     ...
;             const f32x4 cc = tail_sum(parts, 0, 8, tid);
;             const int r = row0 + (tid >> 4), c = col0 + (tid & 15) * 4;
;             const f32x4 h = cc + *(const f32x4*)(x_sample + (size_t)(r - MP) * DM + c);
;             u32x2 w; w.x = cvt_pk_bf16(h[0], h[1]); w.y = cvt_pk_bf16(h[2], h[3]);
;             *(u32x2*)(HP + (size_t)r * LDHP + c) = w;
;             float ss = (h[0] * h[0] + h[1] * h[1]) + (h[2] * h[2] + h[3] * h[3]);
;             ss += __shfl_xor(ss, 1); ss += __shfl_xor(ss, 2); ss += __shfl_xor(ss, 4); ss += __shfl_xor(ss, 8);
;             if ((tid & 15) == 0) SS[(size_t)r * 16 + tn] = ss;
;             __syncthreads();
	s_nop 0
	v_mbcnt_hi_u32_b32 v2, -1, v225
	v_add_u32_e32 v4, s84, v10
	v_and_b32_e32 v10, 64, v2
	v_add_u32_e32 v47, 64, v10
	ds_read_b128 v[10:13], v1
	ds_read_b128 v[14:17], v1 offset:8192
	ds_read_b128 v[18:21], v1 offset:16384
	ds_read_b128 v[22:25], v1 offset:24576
	ds_read_b128 v[26:29], v1 offset:32768
	ds_read_b128 v[30:33], v1 offset:40960
	ds_read_b128 v[34:37], v1 offset:49152
	ds_read_b128 v[38:41], v1 offset:57344
	s_waitcnt lgkmcnt(7)
	v_pk_add_f32 v[12:13], v[12:13], 0 op_sel_hi:[1,0]
	v_pk_add_f32 v[10:11], v[10:11], 0 op_sel_hi:[1,0]
	s_waitcnt lgkmcnt(6)
	v_pk_add_f32 v[12:13], v[12:13], v[16:17]
	v_pk_add_f32 v[10:11], v[10:11], v[14:15]
	s_waitcnt lgkmcnt(5)
	v_pk_add_f32 v[12:13], v[12:13], v[20:21]
	v_pk_add_f32 v[10:11], v[10:11], v[18:19]
	s_waitcnt lgkmcnt(4)
	v_pk_add_f32 v[12:13], v[12:13], v[24:25]
	v_pk_add_f32 v[10:11], v[10:11], v[22:23]
	s_waitcnt lgkmcnt(3)
	v_pk_add_f32 v[12:13], v[12:13], v[28:29]
	v_pk_add_f32 v[10:11], v[10:11], v[26:27]
	s_waitcnt lgkmcnt(2)
	v_pk_add_f32 v[12:13], v[12:13], v[32:33]
	v_pk_add_f32 v[10:11], v[10:11], v[30:31]
	s_waitcnt lgkmcnt(1)
	v_pk_add_f32 v[12:13], v[12:13], v[36:37]
	v_pk_add_f32 v[10:11], v[10:11], v[34:35]
	s_waitcnt lgkmcnt(0)
	v_pk_add_f32 v[12:13], v[12:13], v[40:41]
	v_pk_add_f32 v[10:11], v[10:11], v[38:39]
	v_xor_b32_e32 v5, 1, v2
	v_cmp_lt_i32_e32 vcc, v5, v47
	v_xor_b32_e32 v45, 2, v2
	v_xor_b32_e32 v46, 4, v2
	v_cndmask_b32_e32 v5, v2, v5, vcc
	v_lshlrev_b32_e32 v5, 2, v5
	v_cmp_lt_i32_e32 vcc, v45, v47
	s_nop 0
	s_waitcnt vmcnt(0)
	v_pk_add_f32 v[8:9], v[12:13], v[90:91]
	v_pk_add_f32 v[6:7], v[10:11], v[88:89]
	v_mul_f32_e32 v10, v9, v9
	v_mul_f32_e32 v1, v7, v7
	v_fmac_f32_e32 v1, v6, v6
	v_fmac_f32_e32 v10, v8, v8
	v_add_f32_e32 v1, v1, v10
	ds_bpermute_b32 v5, v5, v1
	v_cndmask_b32_e32 v10, v2, v45, vcc
	v_lshlrev_b32_e32 v10, 2, v10
	v_cmp_lt_i32_e32 vcc, v46, v47
	v_xor_b32_e32 v12, 8, v2
	s_waitcnt lgkmcnt(0)
	v_add_f32_e32 v1, v1, v5
	ds_bpermute_b32 v5, v10, v1
	v_cndmask_b32_e32 v13, v2, v46, vcc
	v_lshlrev_b32_e32 v13, 2, v13
	v_cmp_lt_i32_e32 vcc, v12, v47
	v_mad_i64_i32 v[10:11], s[0:1], v4, s0, v[42:43]
	s_waitcnt lgkmcnt(0)
	v_add_f32_e32 v1, v1, v5
	ds_bpermute_b32 v5, v13, v1
	v_cndmask_b32_e32 v2, v2, v12, vcc
	v_lshlrev_b32_e32 v2, 2, v2
	v_cvt_pk_bf16_f32 v12, v6, v7
	v_cvt_pk_bf16_f32 v13, v8, v9
	s_waitcnt lgkmcnt(0)
	v_add_f32_e32 v1, v1, v5
	ds_bpermute_b32 v6, v2, v1
	v_lshlrev_b32_e32 v2, 1, v44
	v_lshl_add_u64 v[2:3], v[10:11], 0, v[2:3]
	v_cmp_eq_u32_e32 vcc, 0, v80
	global_store_dwordx2 v[2:3], v[12:13], off
	s_and_saveexec_b64 s[0:1], vcc
	s_cbranch_execz .LBB0_887
	s_lshl_b32 s2, s3, 2
	v_ashrrev_i32_e32 v5, 31, v4
	s_add_u32 s2, s8, s2
	s_addc_u32 s3, s9, 0
	v_lshlrev_b64 v[2:3], 6, v[4:5]
	v_lshl_add_u64 v[2:3], s[2:3], 0, v[2:3]
	s_waitcnt lgkmcnt(0)
	v_add_f32_e32 v1, v1, v6
	global_store_dword v[2:3], v1, off
.LBB0_887:
	s_or_b64 exec, exec, s[0:1]
	s_movk_i32 s24, 0x80
	s_waitcnt lgkmcnt(0)
	s_barrier
	s_cmp_eq_u32 s44, 1
	s_cbranch_scc1 .Lp4t_ret

; #define LAS __attribute__((address_space(3)))
; __global__ void __launch_bounds__(NWAVES * 64, 2) fwd_megakernel(Args args) {
;     ...
;         if (G == 256) {
;             const int tm = bx >> 4, tn = bx & 15, row0 = MP + 32 * tm, col0 = 64 * tn, kw = wave * 128;
;             LAS float* parts = (LAS float*)lds;
;             tail_partial<4>(R1 + (size_t)row0 * DM + kw, DM, Wout_t + kw, DM, col0, parts + wave * 2048, lane);
.Lp4c_ret:
	s_waitcnt vmcnt(0)
	s_mov_b64 s[8:9], s[42:43]
	v_mov_b32_e32 v5, v86
	s_barrier
	s_mov_b32 s44, 1
	v_readfirstlane_b32 s2, v0
	s_ashr_i32 s2, s2, 6
	v_mov_b32_e32 v1, v0
	v_mbcnt_lo_u32_b32 v225, -1, 0
	v_readlane_b32 s0, v254, 0
	v_readlane_b32 s1, v254, 1
	s_sub_u32 s0, s0, 0xc0
	s_subb_u32 s1, s1, 0
	s_mov_b64 s[52:53], s[66:67]
	s_load_dwordx2 s[66:67], s[0:1], 0x8
	s_waitcnt lgkmcnt(0)
	s_branch .Lp4t_early
.Lp4t_ret:
	s_waitcnt vmcnt(0)
	s_mov_b64 s[66:67], s[52:53]
